# v3 + P3: per-wave LDS slab for the 7 per-channel parameter vectors (28 global loads per tile -> ds_read_b128), channel-tile-0 weight fragments loaded once into v212-247, waits recomputed from dataflow
# speedup vs baseline: 1.0028x; 1.0028x over previous
; __device__ __forceinline__ void phase3(const P3Args& A, unsigned char* lds, int tid, int wave, int lane) {
;     ...
; #pragma unroll
;             for (int ks = 0; ks < 2; ++ks) { Wd[ks] = *(const bf16x8*)(DUT + (((wave * 4 + 0) * 2 + ks) * 64 + ln) * 8); Wi[ks] = *(const bf16x8*)(IUT + (((wave * 4 + 0) * 2 + ks) * 64 + ln) * 8); }
; #pragma unroll
;             for (int ks = 0; ks < 4; ++ks) Wg[ks] = *(const bf16x8*)(GUT + (((wave * 4 + 0) * 4 + ks) * 64 + ln) * 8);
; #pragma unroll
;             for (int ct = 0; ct < 4; ++ct) {
;                 const int c4 = ct * 16 + fq * 4, ch = wave * 64 + c4;
;                 f32x4 ad = zz, ai = zz, ag = zz;
; #pragma unroll
;                 for (int ks = 0; ks < 2; ++ks) {
;                     ad = __builtin_amdgcn_mfma_f32_16x16x32_bf16(Wd[ks], *(const bf16x8*)(actp + ks * 32), ad, 0, 0, 0);
;                     ai = __builtin_amdgcn_mfma_f32_16x16x32_bf16(Wi[ks], *(const bf16x8*)(actp + 64 + ks * 32), ai, 0, 0, 0);
;                 }
; #pragma unroll
;                 for (int ks = 0; ks < 4; ++ks) ag = __builtin_amdgcn_mfma_f32_16x16x32_bf16(Wg[ks], *(const bf16x8*)(actp + 128 + ks * 32), ag, 0, 0, 0);
;                 if (ct < 3) {
; #pragma unroll
;                     for (int ks = 0; ks < 2; ++ks) { Wd[ks] = *(const bf16x8*)(DUT + (((wave * 4 + ct + 1) * 2 + ks) * 64 + ln) * 8); Wi[ks] = *(const bf16x8*)(IUT + (((wave * 4 + ct + 1) * 2 + ks) * 64 + ln) * 8); }
; #pragma unroll
;                     for (int ks = 0; ks < 4; ++ks) Wg[ks] = *(const bf16x8*)(GUT + (((wave * 4 + ct + 1) * 4 + ks) * 64 + ln) * 8);
;                 }
;                 const f32x4 w0 = *(const f32x4*)(A.w0 + ch), a0 = *(const f32x4*)(A.a0 + ch), ka = *(const f32x4*)(A.k_a + ch), rk = *(const f32x4*)(A.r_k + ch);
;                 const f32x4 mur = *(const f32x4*)(A.mu + ch), muk = *(const f32x4*)(A.mu + 512 + ch), muv = *(const f32x4*)(A.mu + 1024 + ch);
.LBB0_335:
	s_or_b64 exec, exec, s[0:1]
	s_ashr_i32 s0, s41, 31
	s_lshr_b32 s0, s0, 27
	s_add_i32 s0, s41, s0
	s_ashr_i32 s0, s0, 5
	s_lshl_b32 s0, s0, 3
	v_readlane_b32 s1, v242, 17
	s_add_i32 s0, s0, s1
	s_ashr_i32 s7, s6, 31
	s_ashr_i32 s1, s0, 31
	s_lshl_b64 s[4:5], s[0:1], 19
	s_lshl_b64 s[8:9], s[6:7], 7
	s_add_u32 s8, s4, s8
	s_addc_u32 s9, s5, s9
	s_lshl_b64 s[0:1], s[0:1], 20
	s_lshl_b64 s[4:5], s[6:7], 8
	s_add_u32 s10, s0, s4
	s_addc_u32 s11, s1, s5
	s_mov_b32 s12, 16
	v_mbcnt_lo_u32_b32 v211, -1, 0
	v_mbcnt_hi_u32_b32 v211, -1, v211
	v_readlane_b32 s98, v242, 17
	s_lshl_b32 s99, s98, 8
	v_lshl_add_u32 v212, v211, 2, s99
	v_readlane_b32 s100, v241, 38
	v_readlane_b32 s101, v241, 39
	s_nop 4
	global_load_dword v213, v212, s[100:101]
	v_readlane_b32 s100, v241, 32
	v_readlane_b32 s101, v241, 33
	s_nop 4
	global_load_dword v214, v212, s[100:101]
	global_load_dword v215, v212, s[100:101] offset:2048
	v_readlane_b32 s100, v242, 1
	v_readlane_b32 s101, v242, 2
	s_nop 4
	global_load_dword v216, v212, s[100:101]
	v_readlane_b32 s100, v241, 46
	v_readlane_b32 s101, v241, 47
	s_nop 4
	global_load_dword v217, v212, s[100:101]
	v_readlane_b32 s100, v241, 34
	v_readlane_b32 s101, v241, 35
	s_nop 4
	global_load_dword v218, v212, s[100:101]
	global_load_dword v219, v212, s[24:25]
	s_mul_i32 s99, s98, 1792
	s_add_i32 s99, s99, 126464
	v_lshl_add_u32 v220, v211, 2, s99
	s_waitcnt vmcnt(0)
	ds_write_b32 v220, v213
	ds_write_b32 v220, v214 offset:256
	ds_write_b32 v220, v215 offset:512
	ds_write_b32 v220, v216 offset:768
	ds_write_b32 v220, v217 offset:1024
	ds_write_b32 v220, v218 offset:1280
	ds_write_b32 v220, v219 offset:1536
	v_lshrrev_b32_e32 v210, 4, v211
	v_lshl_add_u32 v210, v210, 4, s99
	s_waitcnt lgkmcnt(0)
	v_lshlrev_b32_e32 v195, 3, v109
	v_add_u32_e32 v0, s58, v195
	v_ashrrev_i32_e32 v1, 31, v0
	v_lshlrev_b64 v[4:5], 1, v[0:1]
	v_lshl_add_u64 v[2:3], s[54:55], 0, v[4:5]
	global_load_dwordx4 v[212:215], v[2:3], off
	v_add_u32_e32 v2, s58, v0
	v_ashrrev_i32_e32 v3, 31, v2
	v_add_u32_e32 v0, 0x200, v0
	v_lshl_add_u64 v[6:7], v[2:3], 1, s[60:61]
	v_ashrrev_i32_e32 v1, 31, v0
	global_load_dwordx4 v[216:219], v[6:7], off
	v_lshlrev_b64 v[6:7], 1, v[0:1]
	v_lshl_add_u64 v[0:1], s[54:55], 0, v[6:7]
	v_lshl_add_u64 v[4:5], s[22:23], 0, v[4:5]
	global_load_dwordx4 v[220:223], v[0:1], off
	global_load_dwordx4 v[224:227], v[4:5], off
	v_add_u32_e32 v0, 0x200, v2
	v_ashrrev_i32_e32 v1, 31, v0
	v_lshl_add_u64 v[0:1], v[0:1], 1, s[60:61]
	global_load_dwordx4 v[228:231], v[0:1], off
	v_lshl_add_u64 v[4:5], s[22:23], 0, v[6:7]
	global_load_dwordx4 v[232:235], v[4:5], off
	v_add_u32_e32 v0, 0x400, v2
	v_ashrrev_i32_e32 v1, 31, v0
	v_lshl_add_u64 v[0:1], v[0:1], 1, s[60:61]
	global_load_dwordx4 v[236:239], v[0:1], off
	v_add_u32_e32 v0, 0x600, v2
	v_ashrrev_i32_e32 v1, 31, v0
	v_lshl_add_u64 v[0:1], v[0:1], 1, s[60:61]
	global_load_dwordx4 v[244:247], v[0:1], off
	s_waitcnt vmcnt(0)
	s_branch .LBB0_337

; __device__ __forceinline__ f32x4 bf4(u32x2 w) { return (f32x4){__uint_as_float(w.x << 16), __uint_as_float(w.x & 0xffff0000u), __uint_as_float(w.y << 16), __uint_as_float(w.y & 0xffff0000u)}; }
; __device__ __forceinline__ void phase3(const P3Args& A, unsigned char* lds, int tid, int wave, int lane) {
;     ...
; #pragma unroll
;             for (int ct = 0; ct < 4; ++ct) {
;                 const int c4 = ct * 16 + fq * 4, ch = wave * 64 + c4;
;                 f32x4 ad = zz, ai = zz, ag = zz;
; #pragma unroll
;                 for (int ks = 0; ks < 2; ++ks) {
;                     ad = __builtin_amdgcn_mfma_f32_16x16x32_bf16(Wd[ks], *(const bf16x8*)(actp + ks * 32), ad, 0, 0, 0);
;                     ai = __builtin_amdgcn_mfma_f32_16x16x32_bf16(Wi[ks], *(const bf16x8*)(actp + 64 + ks * 32), ai, 0, 0, 0);
;                 }
; #pragma unroll
;                 for (int ks = 0; ks < 4; ++ks) ag = __builtin_amdgcn_mfma_f32_16x16x32_bf16(Wg[ks], *(const bf16x8*)(actp + 128 + ks * 32), ag, 0, 0, 0);
;                 if (ct < 3) {
; #pragma unroll
;                     for (int ks = 0; ks < 2; ++ks) { Wd[ks] = *(const bf16x8*)(DUT + (((wave * 4 + ct + 1) * 2 + ks) * 64 + ln) * 8); Wi[ks] = *(const bf16x8*)(IUT + (((wave * 4 + ct + 1) * 2 + ks) * 64 + ln) * 8); }
; #pragma unroll
;                     for (int ks = 0; ks < 4; ++ks) Wg[ks] = *(const bf16x8*)(GUT + (((wave * 4 + ct + 1) * 4 + ks) * 64 + ln) * 8);
;                 }
;                 const f32x4 w0 = *(const f32x4*)(A.w0 + ch), a0 = *(const f32x4*)(A.a0 + ch), ka = *(const f32x4*)(A.k_a + ch), rk = *(const f32x4*)(A.r_k + ch);
;                 const f32x4 mur = *(const f32x4*)(A.mu + ch), muk = *(const f32x4*)(A.mu + 512 + ch), muv = *(const f32x4*)(A.mu + 1024 + ch);
;                 const unsigned char* rs = stg + fr * 144 + c4 * 2;
;                 const f32x4 r0 = bf4(*(const u32x2*)(rs)), r1 = bf4(*(const u32x2*)(rs + 144));
;                 const f32x4 k0 = bf4(*(const u32x2*)(rs + 17 * 144)), k1 = bf4(*(const u32x2*)(rs + 18 * 144));
;                 const f32x4 v0 = bf4(*(const u32x2*)(rs + 34 * 144)), v1 = bf4(*(const u32x2*)(rs + 35 * 144));
;                 const f32x4 rm = r1 + (r0 - r1) * mur, km = k1 + (k0 - k1) * muk, vm = v1 + (v0 - v1) * muv;
.LBB0_351:
	s_or_b64 exec, exec, s[6:7]
	v_lshlrev_b32_e32 v195, 3, v116
	v_add_u32_e32 v0, s58, v195
	v_ashrrev_i32_e32 v1, 31, v0
	v_lshlrev_b64 v[4:5], 1, v[0:1]
	s_waitcnt lgkmcnt(0)
	v_lshl_add_u64 v[2:3], s[54:55], 0, v[4:5]
	s_nop 0
	v_add_u32_e32 v2, s58, v0
	v_ashrrev_i32_e32 v3, 31, v2
	v_add_u32_e32 v0, 0x200, v0
	v_lshl_add_u64 v[6:7], v[2:3], 1, s[60:61]
	v_ashrrev_i32_e32 v1, 31, v0
	s_nop 0
	v_lshlrev_b64 v[6:7], 1, v[0:1]
	v_lshl_add_u64 v[0:1], s[54:55], 0, v[6:7]
	v_lshl_add_u64 v[4:5], s[22:23], 0, v[4:5]
	s_nop 0
	s_nop 0
	v_add_u32_e32 v0, 0x200, v2
	v_ashrrev_i32_e32 v1, 31, v0
	v_lshl_add_u64 v[0:1], v[0:1], 1, s[60:61]
	s_nop 0
	v_lshl_add_u64 v[4:5], s[22:23], 0, v[6:7]
	s_nop 0
	v_add_u32_e32 v0, 0x400, v2
	v_ashrrev_i32_e32 v1, 31, v0
	v_lshl_add_u64 v[0:1], v[0:1], 1, s[60:61]
	s_nop 0
	v_add_u32_e32 v0, 0x600, v2
	v_ashrrev_i32_e32 v1, 31, v0
	v_lshl_add_u64 v[0:1], v[0:1], 1, s[60:61]
	s_nop 0
	v_add_u32_e32 v21, v20, v123
	v_lshlrev_b32_e32 v171, 2, v21
	v_add_u32_e32 v28, s34, v171
	v_ashrrev_i32_e32 v29, 31, v28
	v_lshlrev_b64 v[90:91], 2, v[28:29]
	v_lshl_add_u64 v[100:101], s[70:71], 0, v[90:91]
	ds_read_b128 v[28:31], v210 offset:0
	v_add_u32_e32 v180, v20, v121
	v_add_u32_e32 v23, s12, v180
	s_nop 0
	v_mul_lo_u32 v48, v23, s90
	v_add_u32_e32 v20, v125, v20
	v_lshlrev_b32_e32 v181, 4, v21
	v_add_u32_e32 v44, s16, v195
	v_add_u32_e32 v46, s18, v195
	v_add_u32_e32 v50, 0, v48
	s_movk_i32 s6, 0xdf00
	v_add3_u32 v56, v20, s12, -16
	v_mul_lo_u32 v25, v180, s3
	v_add_u32_e32 v20, s59, v195
	v_add_u32_e32 v22, s62, v195
	v_add_u32_e32 v24, s56, v195
	v_add_u32_e32 v26, s63, v195
	v_ashrrev_i32_e32 v45, 31, v44
	v_ashrrev_i32_e32 v47, 31, v46
	v_add3_u32 v172, v50, v181, s6
	v_lshlrev_b32_e32 v57, 3, v21
	v_cmp_eq_u32_e64 s[52:53], 0, v21
	v_add_u32_e32 v170, s39, v25
	v_ashrrev_i32_e32 v21, 31, v20
	v_ashrrev_i32_e32 v23, 31, v22
	v_ashrrev_i32_e32 v25, 31, v24
	v_ashrrev_i32_e32 v27, 31, v26
	v_lshl_add_u64 v[70:71], v[44:45], 1, s[60:61]
	v_lshl_add_u64 v[72:73], v[46:47], 1, s[60:61]
	ds_read_b128 v[44:47], v172 offset:128
	v_lshlrev_b64 v[20:21], 1, v[20:21]
	v_lshlrev_b64 v[22:23], 1, v[22:23]
	v_lshl_add_u64 v[24:25], v[24:25], 1, s[60:61]
	v_lshl_add_u64 v[48:49], v[26:27], 1, s[60:61]
	v_lshl_add_u64 v[92:93], s[22:23], 0, v[20:21]
	v_lshl_add_u64 v[94:95], s[54:55], 0, v[20:21]
	v_lshl_add_u64 v[96:97], s[22:23], 0, v[22:23]
	v_lshl_add_u64 v[98:99], s[54:55], 0, v[22:23]
	global_load_dwordx4 v[24:27], v[24:25], off
	s_nop 0
	global_load_dwordx4 v[20:23], v[48:49], off
	ds_read_b128 v[48:51], v172 offset:192
	ds_read_b128 v[52:55], v172 offset:256
	ds_read_b128 v[58:61], v172 offset:320
	v_lshl_add_u64 v[102:103], s[64:65], 0, v[90:91]
	v_lshl_add_u64 v[104:105], s[78:79], 0, v[90:91]
	ds_read_b128 v[62:65], v210 offset:256
	ds_read_b128 v[66:69], v210 offset:512
	v_readlane_b32 s64, v242, 1
	v_readlane_b32 s65, v242, 2
	v_readlane_b32 s66, v242, 3
	v_readlane_b32 s67, v242, 4
	v_lshl_add_u64 v[106:107], s[64:65], 0, v[90:91]
	v_readlane_b32 s68, v242, 5
	v_readlane_b32 s69, v242, 6
	v_readlane_b32 s70, v242, 7
	v_readlane_b32 s71, v242, 8
	s_nop 0
	s_nop 0
	s_waitcnt lgkmcnt(5)
	v_mfma_f32_16x16x32_bf16 v[44:47], v[212:215], v[44:47], 0
	v_readlane_b32 s72, v242, 9
	v_readlane_b32 s73, v242, 10
	v_readlane_b32 s74, v242, 11
	s_nop 0
	s_nop 0
	s_waitcnt lgkmcnt(3)
	v_mfma_f32_16x16x32_bf16 v[52:55], v[216:219], v[52:55], 0
	global_load_dwordx4 v[36:39], v[70:71], off
	global_load_dwordx4 v[32:35], v[72:73], off
	ds_read_b128 v[78:81], v210 offset:768
	v_readlane_b32 s75, v242, 12
	ds_read_b128 v[70:73], v210 offset:1024
	s_nop 0
	s_nop 0
	v_mfma_f32_16x16x32_bf16 v[74:77], v[220:223], v[48:51], v[44:47]
	ds_read_b128 v[40:43], v172 offset:384
	v_readlane_b32 s76, v242, 13
	v_readlane_b32 s77, v242, 14
	s_nop 0
	s_nop 0
	s_waitcnt lgkmcnt(5)
	v_mfma_f32_16x16x32_bf16 v[12:15], v[228:231], v[58:61], v[52:55]
	ds_read_b128 v[58:61], v172
	ds_read_b128 v[82:85], v172 offset:64
	ds_read_b128 v[86:89], v172 offset:448
	v_readlane_b32 s78, v242, 15
	v_readlane_b32 s79, v242, 16
	s_nop 0
	s_nop 0
	s_waitcnt lgkmcnt(3)
	v_mfma_f32_16x16x32_bf16 v[8:11], v[236:239], v[40:43], v[12:15]
	v_readlane_b32 s64, v241, 32
	v_readlane_b32 s66, v241, 34
	v_readlane_b32 s67, v241, 35
	global_load_dwordx4 v[44:47], v[92:93], off
	global_load_dwordx4 v[40:43], v[94:95], off
	global_load_dwordx4 v[52:55], v[96:97], off
	global_load_dwordx4 v[48:51], v[98:99], off
	v_lshl_add_u64 v[168:169], s[66:67], 0, v[90:91]
	v_lshl_add_u64 v[12:13], s[24:25], 0, v[90:91]
	s_nop 0
	s_nop 0
	s_waitcnt lgkmcnt(0)
	v_mfma_f32_16x16x32_bf16 v[8:11], v[244:247], v[86:89], v[8:11]
	ds_read_b128 v[0:3], v210 offset:1280
	s_nop 0
	v_add_f32_e32 v28, v74, v28
	ds_read_b128 v[12:15], v210 offset:1536
	v_mul_f32_e32 v28, 0xbfb8aa3b, v28
	v_add_f32_e32 v29, v75, v29
	v_exp_f32_e32 v28, v28
	v_mul_f32_e32 v29, 0xbfb8aa3b, v29
	v_exp_f32_e32 v29, v29
	v_mfma_f32_16x16x32_bf16 v[16:19], v[224:227], v[58:61], 0
	v_add_f32_e32 v28, 1.0, v28
	v_rcp_f32_e32 v130, v28
	v_add_f32_e32 v28, 1.0, v29
	v_add_f32_e32 v29, v76, v30
	v_mul_f32_e32 v29, 0xbfb8aa3b, v29
	v_add_f32_e32 v30, v77, v31
	v_exp_f32_e32 v29, v29
	v_mul_f32_e32 v30, 0xbfb8aa3b, v30
	v_exp_f32_e32 v30, v30
	v_add_u32_e32 v182, v170, v57
	v_mfma_f32_16x16x32_bf16 v[4:7], v[232:235], v[82:85], v[16:19]
	ds_read2_b64 v[58:61], v182 offset1:18
	v_rcp_f32_e32 v131, v28
	v_add_f32_e32 v28, 1.0, v29
	v_add_u32_e32 v16, 0x800, v182
	ds_read2_b64 v[16:19], v16 offset0:50 offset1:68
	v_rcp_f32_e32 v132, v28
	v_add_f32_e32 v28, 1.0, v30
	v_rcp_f32_e32 v133, v28
	v_ashrrev_i32_e32 v57, 31, v56
	v_lshlrev_b64 v[56:57], 7, v[56:57]
	v_lshl_add_u64 v[154:155], s[20:21], 0, v[56:57]
	s_nop 0
	s_nop 0
	s_waitcnt lgkmcnt(1)
; __device__ __forceinline__ unsigned pk2(float lo, float hi) { f32x2_t v = {lo, hi}; bf16x2_t b = __builtin_convertvector(v, bf16x2_t); return __builtin_bit_cast(unsigned, b); }
; __device__ __forceinline__ void phase3(const P3Args& A, unsigned char* lds, int tid, int wave, int lane) {
;     ...
;                 if (ct < 3) {
; #pragma unroll
;                     for (int ks = 0; ks < 2; ++ks) { Wd[ks] = *(const bf16x8*)(DUT + (((wave * 4 + ct + 1) * 2 + ks) * 64 + ln) * 8); Wi[ks] = *(const bf16x8*)(IUT + (((wave * 4 + ct + 1) * 2 + ks) * 64 + ln) * 8); }
; #pragma unroll
;                     for (int ks = 0; ks < 4; ++ks) Wg[ks] = *(const bf16x8*)(GUT + (((wave * 4 + ct + 1) * 4 + ks) * 64 + ln) * 8);
;                 }
;                 const f32x4 w0 = *(const f32x4*)(A.w0 + ch), a0 = *(const f32x4*)(A.a0 + ch), ka = *(const f32x4*)(A.k_a + ch), rk = *(const f32x4*)(A.r_k + ch);
;                 const f32x4 mur = *(const f32x4*)(A.mu + ch), muk = *(const f32x4*)(A.mu + 512 + ch), muv = *(const f32x4*)(A.mu + 1024 + ch);
;                 const unsigned char* rs = stg + fr * 144 + c4 * 2;
;                 const f32x4 r0 = bf4(*(const u32x2*)(rs)), r1 = bf4(*(const u32x2*)(rs + 144));
;                 const f32x4 k0 = bf4(*(const u32x2*)(rs + 17 * 144)), k1 = bf4(*(const u32x2*)(rs + 18 * 144));
;                 const f32x4 v0 = bf4(*(const u32x2*)(rs + 34 * 144)), v1 = bf4(*(const u32x2*)(rs + 35 * 144));
;                 const f32x4 rm = r1 + (r0 - r1) * mur, km = k1 + (k0 - k1) * muk, vm = v1 + (v0 - v1) * muv;
;                 f32x4 lw, ah;
; #pragma unroll
;                 for (int r = 0; r < 4; ++r) { lw[r] = -0.6065306597f * sigmoidf_(w0[r] + ad[r]); ah[r] = sigmoidf_(a0[r] + ai[r]); }
;                 const f32x4 kp = km * ((ah - 1.0f) * ka + 1.0f);
;                 const f32x4 pr3 = rm * kp * rk;
;                 float rks = (pr3[0] + pr3[1]) + (pr3[2] + pr3[3]);
;                 rks = rows4_sum(rks);
;                 if (fq == 0) RK[((size_t)t * 8 + wave) * 4 + ct] = rks;
;                 lwo[ct] = lw;
;                 ro[ct] = (u32x2){pk2(rm[0], rm[1]), pk2(rm[2], rm[3])}; ko[ct] = (u32x2){pk2(km[0], km[1]), pk2(km[2], km[3])};
;                 vo[ct] = (u32x2){pk2(vm[0], vm[1]), pk2(vm[2], vm[3])}; aho[ct] = (u32x2){pk2(ah[0], ah[1]), pk2(ah[2], ah[3])};
;                 go[ct] = (u32x2){pk2(ag[0], ag[1]), pk2(ag[2], ag[3])};
	v_lshlrev_b32_e32 v86, 16, v58
	v_and_b32_e32 v87, 0xffff0000, v58
	v_lshlrev_b32_e32 v84, 16, v59
	v_and_b32_e32 v85, 0xffff0000, v59
	v_lshlrev_b32_e32 v56, 16, v60
	v_and_b32_e32 v57, 0xffff0000, v60
	v_lshlrev_b32_e32 v58, 16, v61
	v_and_b32_e32 v59, 0xffff0000, v61
	s_nop 0
	s_nop 0
	s_waitcnt lgkmcnt(0)
	v_lshlrev_b32_e32 v90, 16, v16
	v_and_b32_e32 v91, 0xffff0000, v16
	v_lshlrev_b32_e32 v88, 16, v17
	v_and_b32_e32 v89, 0xffff0000, v17
	v_lshlrev_b32_e32 v60, 16, v18
	v_and_b32_e32 v61, 0xffff0000, v18
	v_lshlrev_b32_e32 v82, 16, v19
	v_and_b32_e32 v83, 0xffff0000, v19
	v_sub_f32_e32 v89, v89, v83
	v_sub_f32_e32 v88, v88, v82
	v_sub_f32_e32 v91, v91, v61
	v_sub_f32_e32 v90, v90, v60
	v_pk_add_f32 v[28:29], v[132:133], -1.0 op_sel_hi:[1,0]
	v_pk_add_f32 v[30:31], v[130:131], -1.0 op_sel_hi:[1,0]
	v_sub_f32_e32 v85, v85, v59
	v_sub_f32_e32 v84, v84, v58
	v_sub_f32_e32 v87, v87, v57
	v_sub_f32_e32 v86, v86, v56
	s_nop 0
	v_pk_fma_f32 v[138:139], v[66:67], v[90:91], v[60:61]
	v_pk_fma_f32 v[140:141], v[68:69], v[88:89], v[82:83]
	v_pk_fma_f32 v[134:135], v[62:63], v[86:87], v[56:57]
	v_pk_fma_f32 v[136:137], v[64:65], v[84:85], v[58:59]
	s_nop 0
	v_pk_fma_f32 v[30:31], v[70:71], v[30:31], 1.0 op_sel_hi:[1,1,0]
	v_pk_fma_f32 v[28:29], v[72:73], v[28:29], 1.0 op_sel_hi:[1,1,0]
	v_pk_mul_f32 v[30:31], v[30:31], v[138:139]
	v_pk_mul_f32 v[28:29], v[28:29], v[140:141]
	v_pk_mul_f32 v[30:31], v[134:135], v[30:31]
	v_pk_mul_f32 v[28:29], v[136:137], v[28:29]
	v_pk_mul_f32 v[30:31], v[78:79], v[30:31]
	v_pk_mul_f32 v[28:29], v[80:81], v[28:29]
	v_add_f32_e32 v30, v30, v31
	v_add_f32_e32 v28, v28, v29
	v_add_u32_e32 v16, 0x1000, v182
	v_add_f32_e32 v28, v30, v28
	ds_read2_b64 v[16:19], v16 offset0:100 offset1:118
	v_mov_b32_e32 v29, v28
	s_nop 1
	v_permlane32_swap_b32_e32 v28, v29
	v_add_f32_e32 v28, v28, v29
	v_mov_b32_e32 v29, v28
	v_readlane_b32 s65, v241, 33
	v_readlane_b32 s70, v241, 38
	v_readlane_b32 s71, v241, 39
	v_readlane_b32 s78, v241, 46
	v_readlane_b32 s79, v241, 47
	v_permlane16_swap_b32_e32 v28, v29
	v_readlane_b32 s68, v241, 36
	v_readlane_b32 s69, v241, 37
	v_readlane_b32 s72, v241, 40
	v_readlane_b32 s73, v241, 41
	v_readlane_b32 s74, v241, 42
	v_readlane_b32 s75, v241, 43
	v_readlane_b32 s76, v241, 44
	v_readlane_b32 s77, v241, 45
	s_and_saveexec_b64 s[6:7], s[52:53]
	s_cbranch_execz .LBB0_353
	v_add_f32_e32 v28, v28, v29
	global_store_dword v[154:155], v28, off
.LBB0_353:
	s_or_b64 exec, exec, s[6:7]
	ds_read_b128 v[28:31], v172 offset:128
	ds_read_b128 v[56:59], v172 offset:192
	ds_read_b128 v[84:87], v210 offset:64
	v_add_u32_e32 v142, 16, v171
	s_nop 0
	s_nop 0
	s_waitcnt vmcnt(2) lgkmcnt(2)
	v_mfma_f32_16x16x32_bf16 v[28:31], v[40:43], v[28:31], 0
	ds_read_b128 v[40:43], v172 offset:256
	s_nop 0
	s_nop 0
	s_waitcnt vmcnt(0) lgkmcnt(2)
	v_mfma_f32_16x16x32_bf16 v[80:83], v[48:51], v[56:59], v[28:31]
	s_nop 4
	ds_read_b128 v[28:31], v172 offset:320
	s_nop 0
	s_nop 0
	s_waitcnt lgkmcnt(1)
	v_mfma_f32_16x16x32_bf16 v[24:27], v[24:27], v[40:43], 0
	ds_read_b128 v[88:91], v172
	ds_read_b128 v[92:95], v172 offset:64
	ds_read_b128 v[40:43], v172 offset:384
	ds_read_b128 v[48:51], v172 offset:448
	s_nop 0
	v_add_f32_e32 v80, v80, v84
	s_nop 0
	s_nop 0
	s_waitcnt lgkmcnt(4)
	v_mfma_f32_16x16x32_bf16 v[20:23], v[20:23], v[28:31], v[24:27]
	v_mul_f32_e32 v80, 0xbfb8aa3b, v80
	v_add_f32_e32 v81, v81, v85
	v_exp_f32_e32 v80, v80
	s_nop 0
	s_nop 0
	s_waitcnt lgkmcnt(1)
	v_mfma_f32_16x16x32_bf16 v[20:23], v[36:39], v[40:43], v[20:23]
	v_add_u32_e32 v26, s19, v195
	v_ashrrev_i32_e32 v27, 31, v26
	v_lshlrev_b64 v[26:27], 1, v[26:27]
	s_nop 0
	s_nop 0
	s_waitcnt lgkmcnt(0)
	v_mfma_f32_16x16x32_bf16 v[28:31], v[32:35], v[48:51], v[20:23]
	v_lshl_add_u64 v[36:37], s[22:23], 0, v[26:27]
	v_lshl_add_u64 v[26:27], s[54:55], 0, v[26:27]
	global_load_dwordx4 v[40:43], v[36:37], off
	global_load_dwordx4 v[72:75], v[26:27], off
	v_add_u32_e32 v20, s36, v195
	v_ashrrev_i32_e32 v21, 31, v20
	v_lshlrev_b64 v[20:21], 1, v[20:21]
	v_lshl_add_u64 v[22:23], s[22:23], 0, v[20:21]
	v_lshl_add_u64 v[20:21], s[54:55], 0, v[20:21]
	ds_read_b128 v[96:99], v210 offset:320
	global_load_dwordx4 v[48:51], v[22:23], off
	global_load_dwordx4 v[76:79], v[20:21], off
	ds_read_b128 v[156:159], v210 offset:576
	v_add_u32_e32 v20, s57, v195
	ds_read_b128 v[160:163], v210 offset:1088
	v_ashrrev_i32_e32 v21, 31, v20
	v_add_u32_e32 v22, s40, v195
	v_lshl_add_u64 v[20:21], v[20:21], 1, s[60:61]
	v_ashrrev_i32_e32 v23, 31, v22
	v_lshl_add_u64 v[22:23], v[22:23], 1, s[60:61]
	global_load_dwordx4 v[68:71], v[20:21], off
	global_load_dwordx4 v[56:59], v[22:23], off
	ds_read_b128 v[164:167], v210 offset:832
	v_add_u32_e32 v24, s34, v142
	v_add_u32_e32 v20, s80, v195
	v_add_u32_e32 v22, s81, v195
	v_ashrrev_i32_e32 v21, 31, v20
	v_ashrrev_i32_e32 v23, 31, v22
	v_ashrrev_i32_e32 v25, 31, v24
	v_lshl_add_u64 v[20:21], v[20:21], 1, s[60:61]
	v_lshl_add_u64 v[22:23], v[22:23], 1, s[60:61]
	v_lshl_add_u64 v[24:25], v[24:25], 2, s[24:25]
	global_load_dwordx4 v[64:67], v[20:21], off
	global_load_dwordx4 v[60:63], v[22:23], off
	ds_read_b128 v[32:35], v210 offset:1600
	v_mfma_f32_16x16x32_bf16 v[24:27], v[44:47], v[88:91], 0
	ds_read_b128 v[20:23], v210 offset:1344
	v_lshl_add_u32 v88, v142, 1, v170
	ds_read2_b64 v[36:39], v88 offset1:18
	v_mul_f32_e32 v81, 0xbfb8aa3b, v81
	v_exp_f32_e32 v81, v81
	v_mfma_f32_16x16x32_bf16 v[24:27], v[52:55], v[92:95], v[24:27]
	v_add_f32_e32 v80, 1.0, v80
	s_nop 0
	s_nop 0
	s_waitcnt lgkmcnt(0)
; __device__ __forceinline__ void phase3(const P3Args& A, unsigned char* lds, int tid, int wave, int lane) {
;     ...
;             for (int ct = 0; ct < 4; ++ct) {
;                 const int c4 = ct * 16 + fq * 4, ch = wave * 64 + c4;
;                 f32x4 ad = zz, ai = zz, ag = zz;
; #pragma unroll
;                 for (int ks = 0; ks < 2; ++ks) {
;                     ad = __builtin_amdgcn_mfma_f32_16x16x32_bf16(Wd[ks], *(const bf16x8*)(actp + ks * 32), ad, 0, 0, 0);
;                     ai = __builtin_amdgcn_mfma_f32_16x16x32_bf16(Wi[ks], *(const bf16x8*)(actp + 64 + ks * 32), ai, 0, 0, 0);
;                 }
; #pragma unroll
;                 for (int ks = 0; ks < 4; ++ks) ag = __builtin_amdgcn_mfma_f32_16x16x32_bf16(Wg[ks], *(const bf16x8*)(actp + 128 + ks * 32), ag, 0, 0, 0);
;                 if (ct < 3) {
; #pragma unroll
;                     for (int ks = 0; ks < 2; ++ks) { Wd[ks] = *(const bf16x8*)(DUT + (((wave * 4 + ct + 1) * 2 + ks) * 64 + ln) * 8); Wi[ks] = *(const bf16x8*)(IUT + (((wave * 4 + ct + 1) * 2 + ks) * 64 + ln) * 8); }
; #pragma unroll
;                     for (int ks = 0; ks < 4; ++ks) Wg[ks] = *(const bf16x8*)(GUT + (((wave * 4 + ct + 1) * 4 + ks) * 64 + ln) * 8);
;                 }
;                 const f32x4 w0 = *(const f32x4*)(A.w0 + ch), a0 = *(const f32x4*)(A.a0 + ch), ka = *(const f32x4*)(A.k_a + ch), rk = *(const f32x4*)(A.r_k + ch);
;                 const f32x4 mur = *(const f32x4*)(A.mu + ch), muk = *(const f32x4*)(A.mu + 512 + ch), muv = *(const f32x4*)(A.mu + 1024 + ch);
;                 const unsigned char* rs = stg + fr * 144 + c4 * 2;
;                 const f32x4 r0 = bf4(*(const u32x2*)(rs)), r1 = bf4(*(const u32x2*)(rs + 144));
;                 const f32x4 k0 = bf4(*(const u32x2*)(rs + 17 * 144)), k1 = bf4(*(const u32x2*)(rs + 18 * 144));
;                 const f32x4 v0 = bf4(*(const u32x2*)(rs + 34 * 144)), v1 = bf4(*(const u32x2*)(rs + 35 * 144));
;                 const f32x4 rm = r1 + (r0 - r1) * mur, km = k1 + (k0 - k1) * muk, vm = v1 + (v0 - v1) * muv;
;                 f32x4 lw, ah;
; #pragma unroll
;                 for (int r = 0; r < 4; ++r) { lw[r] = -0.6065306597f * sigmoidf_(w0[r] + ad[r]); ah[r] = sigmoidf_(a0[r] + ai[r]); }
;                 const f32x4 kp = km * ((ah - 1.0f) * ka + 1.0f);
;                 const f32x4 pr3 = rm * kp * rk;
	v_lshlrev_b32_e32 v90, 16, v36
	v_and_b32_e32 v89, 0xffff0000, v36
	v_add_u32_e32 v36, 0x800, v88
	ds_read2_b64 v[44:47], v36 offset0:50 offset1:68
	v_lshlrev_b32_e32 v92, 16, v37
	v_lshlrev_b32_e32 v52, 16, v38
	v_lshlrev_b32_e32 v54, 16, v39
	v_add_u32_e32 v36, 0x1000, v88
	s_nop 0
	s_nop 0
	s_waitcnt lgkmcnt(0)
	v_lshlrev_b32_e32 v94, 16, v44
	v_and_b32_e32 v93, 0xffff0000, v44
	v_lshlrev_b32_e32 v142, 16, v45
	v_and_b32_e32 v95, 0xffff0000, v45
	v_lshlrev_b32_e32 v44, 16, v46
	v_and_b32_e32 v45, 0xffff0000, v46
	v_lshlrev_b32_e32 v46, 16, v47
	v_sub_f32_e32 v88, v90, v52
	v_sub_f32_e32 v90, v92, v54
	v_sub_f32_e32 v92, v94, v44
	v_sub_f32_e32 v94, v142, v46
	v_rcp_f32_e32 v142, v80
	v_add_f32_e32 v80, 1.0, v81
	v_add_f32_e32 v81, v82, v86
	v_mul_f32_e32 v81, 0xbfb8aa3b, v81
	v_add_f32_e32 v82, v83, v87
	v_exp_f32_e32 v81, v81
	v_mul_f32_e32 v82, 0xbfb8aa3b, v82
	v_exp_f32_e32 v82, v82
	v_rcp_f32_e32 v143, v80
	v_add_f32_e32 v80, 1.0, v81
	v_rcp_f32_e32 v144, v80
	v_add_f32_e32 v80, 1.0, v82
	v_rcp_f32_e32 v145, v80
	v_and_b32_e32 v47, 0xffff0000, v47
	v_sub_f32_e32 v93, v93, v45
	v_sub_f32_e32 v95, v95, v47
	v_and_b32_e32 v91, 0xffff0000, v37
	v_and_b32_e32 v53, 0xffff0000, v38
	v_and_b32_e32 v55, 0xffff0000, v39
	v_sub_f32_e32 v89, v89, v53
	v_sub_f32_e32 v91, v91, v55
	ds_read2_b64 v[36:39], v36 offset0:100 offset1:118
	s_nop 0
	v_pk_fma_f32 v[146:147], v[98:99], v[90:91], v[54:55]
	v_pk_fma_f32 v[148:149], v[96:97], v[88:89], v[52:53]
	s_nop 0
	v_pk_fma_f32 v[150:151], v[158:159], v[94:95], v[46:47]
	v_pk_fma_f32 v[152:153], v[156:157], v[92:93], v[44:45]
	v_pk_add_f32 v[44:45], v[144:145], -1.0 op_sel_hi:[1,0]
	v_pk_add_f32 v[46:47], v[142:143], -1.0 op_sel_hi:[1,0]
	s_nop 0
	v_pk_fma_f32 v[44:45], v[162:163], v[44:45], 1.0 op_sel_hi:[1,1,0]
	v_pk_fma_f32 v[46:47], v[160:161], v[46:47], 1.0 op_sel_hi:[1,1,0]
	v_pk_mul_f32 v[44:45], v[44:45], v[150:151]
	v_pk_mul_f32 v[46:47], v[46:47], v[152:153]
	v_pk_mul_f32 v[44:45], v[146:147], v[44:45]
	v_pk_mul_f32 v[46:47], v[148:149], v[46:47]
	s_nop 0
	v_pk_mul_f32 v[44:45], v[166:167], v[44:45]
	v_pk_mul_f32 v[46:47], v[164:165], v[46:47]
	v_add_f32_e32 v44, v44, v45
	v_add_f32_e32 v46, v46, v47
	v_add_f32_e32 v44, v46, v44
	v_mov_b32_e32 v45, v44
	s_nop 1
	v_permlane32_swap_b32_e32 v44, v45
	v_add_f32_e32 v44, v44, v45
	v_mov_b32_e32 v45, v44
	s_nop 1
	v_permlane16_swap_b32_e32 v44, v45
	s_and_saveexec_b64 s[6:7], s[52:53]
	s_cbranch_execz .LBB0_355
	v_add_f32_e32 v44, v44, v45
	global_store_dword v[154:155], v44, off offset:4
.LBB0_355:
	s_or_b64 exec, exec, s[6:7]
	ds_read_b128 v[44:47], v172 offset:128
	ds_read_b128 v[52:55], v172 offset:192
	ds_read_b128 v[160:163], v210 offset:128
	v_add_u32_e32 v173, 32, v171
	s_nop 0
	s_nop 0
	s_waitcnt vmcnt(6) lgkmcnt(2)
	v_mfma_f32_16x16x32_bf16 v[44:47], v[72:75], v[44:47], 0
	ds_read_b128 v[72:75], v172 offset:256
	s_nop 0
	s_nop 0
	s_waitcnt vmcnt(4) lgkmcnt(2)
	v_mfma_f32_16x16x32_bf16 v[156:159], v[76:79], v[52:55], v[44:47]
	s_nop 4
	ds_read_b128 v[44:47], v172 offset:320
	s_nop 0
	s_nop 0
	s_waitcnt vmcnt(3) lgkmcnt(1)
	v_mfma_f32_16x16x32_bf16 v[52:55], v[68:71], v[72:75], 0
	ds_read_b128 v[68:71], v172
	ds_read_b128 v[164:167], v172 offset:64
	ds_read_b128 v[72:75], v172 offset:384
	ds_read_b128 v[76:79], v172 offset:448
	s_nop 0
	v_add_f32_e32 v156, v156, v160
	s_nop 0
	s_nop 0
	s_waitcnt vmcnt(2) lgkmcnt(4)
	v_mfma_f32_16x16x32_bf16 v[44:47], v[56:59], v[44:47], v[52:55]
	v_add_f32_e32 v157, v157, v161
	v_add_f32_e32 v158, v158, v162
	v_add_f32_e32 v159, v159, v163
	s_nop 0
	s_nop 0
	s_waitcnt vmcnt(1) lgkmcnt(1)
	v_mfma_f32_16x16x32_bf16 v[44:47], v[64:67], v[72:75], v[44:47]
	v_add_u32_e32 v54, s82, v195
	v_ashrrev_i32_e32 v55, 31, v54
	v_lshlrev_b64 v[54:55], 1, v[54:55]
	s_nop 0
	s_nop 0
	s_waitcnt vmcnt(0) lgkmcnt(0)
	v_mfma_f32_16x16x32_bf16 v[56:59], v[60:63], v[76:79], v[44:47]
	v_lshl_add_u64 v[64:65], s[22:23], 0, v[54:55]
	v_lshl_add_u64 v[54:55], s[54:55], 0, v[54:55]
	global_load_dwordx4 v[72:75], v[64:65], off
	global_load_dwordx4 v[60:63], v[54:55], off
	v_add_u32_e32 v44, s83, v195
	v_ashrrev_i32_e32 v45, 31, v44
	v_lshlrev_b64 v[44:45], 1, v[44:45]
	v_lshl_add_u64 v[46:47], s[22:23], 0, v[44:45]
	v_lshl_add_u64 v[44:45], s[54:55], 0, v[44:45]
	ds_read_b128 v[174:177], v210 offset:384
	global_load_dwordx4 v[76:79], v[46:47], off
	global_load_dwordx4 v[80:83], v[44:45], off
	ds_read_b128 v[196:199], v210 offset:640
	v_add_u32_e32 v44, s84, v195
	ds_read_b128 v[200:203], v210 offset:1152
	v_ashrrev_i32_e32 v45, 31, v44
	v_add_u32_e32 v46, s85, v195
	v_lshl_add_u64 v[44:45], v[44:45], 1, s[60:61]
	v_ashrrev_i32_e32 v47, 31, v46
	v_lshl_add_u64 v[46:47], v[46:47], 1, s[60:61]
	global_load_dwordx4 v[88:91], v[44:45], off
	global_load_dwordx4 v[84:87], v[46:47], off
	ds_read_b128 v[204:207], v210 offset:896
	v_add_u32_e32 v52, s34, v173
	v_add_u32_e32 v44, s86, v195
	v_add_u32_e32 v46, s87, v195
	v_ashrrev_i32_e32 v45, 31, v44
	v_ashrrev_i32_e32 v47, 31, v46
	v_ashrrev_i32_e32 v53, 31, v52
	v_lshl_add_u64 v[44:45], v[44:45], 1, s[60:61]
	v_lshl_add_u64 v[46:47], v[46:47], 1, s[60:61]
	v_lshl_add_u64 v[52:53], v[52:53], 2, s[24:25]
	global_load_dwordx4 v[96:99], v[44:45], off
	global_load_dwordx4 v[92:95], v[46:47], off
	ds_read_b128 v[64:67], v210 offset:1664
	v_mfma_f32_16x16x32_bf16 v[40:43], v[40:43], v[68:71], 0
	ds_read_b128 v[44:47], v210 offset:1408
	v_mul_f32_e32 v156, 0xbfb8aa3b, v156
	v_mul_f32_e32 v157, 0xbfb8aa3b, v157
	v_mul_f32_e32 v158, 0xbfb8aa3b, v158
	v_mul_f32_e32 v159, 0xbfb8aa3b, v159
	v_lshl_add_u32 v173, v173, 1, v170
	v_exp_f32_e32 v156, v156
	v_exp_f32_e32 v157, v157
	v_exp_f32_e32 v158, v158
	v_exp_f32_e32 v159, v159
	v_mfma_f32_16x16x32_bf16 v[52:55], v[48:51], v[164:167], v[40:43]
	ds_read2_b64 v[68:71], v173 offset1:18
	v_add_f32_e32 v156, 1.0, v156
	v_add_f32_e32 v157, 1.0, v157
	v_add_u32_e32 v40, 0x800, v173
	ds_read2_b64 v[40:43], v40 offset0:50 offset1:68
	v_add_f32_e32 v158, 1.0, v158
	v_add_f32_e32 v159, 1.0, v159
	v_rcp_f32_e32 v156, v156
	v_rcp_f32_e32 v157, v157
	v_rcp_f32_e32 v158, v158
	v_rcp_f32_e32 v159, v159
	s_nop 0
	s_nop 0
	s_waitcnt lgkmcnt(1)
; __device__ __forceinline__ void phase3(const P3Args& A, unsigned char* lds, int tid, int wave, int lane) {
;     ...
;             for (int ct = 0; ct < 4; ++ct) {
;                 const int c4 = ct * 16 + fq * 4, ch = wave * 64 + c4;
;                 f32x4 ad = zz, ai = zz, ag = zz;
; #pragma unroll
;                 for (int ks = 0; ks < 2; ++ks) {
;                     ad = __builtin_amdgcn_mfma_f32_16x16x32_bf16(Wd[ks], *(const bf16x8*)(actp + ks * 32), ad, 0, 0, 0);
;                     ai = __builtin_amdgcn_mfma_f32_16x16x32_bf16(Wi[ks], *(const bf16x8*)(actp + 64 + ks * 32), ai, 0, 0, 0);
;                 }
; #pragma unroll
;                 for (int ks = 0; ks < 4; ++ks) ag = __builtin_amdgcn_mfma_f32_16x16x32_bf16(Wg[ks], *(const bf16x8*)(actp + 128 + ks * 32), ag, 0, 0, 0);
;                 if (ct < 3) {
; #pragma unroll
;                     for (int ks = 0; ks < 2; ++ks) { Wd[ks] = *(const bf16x8*)(DUT + (((wave * 4 + ct + 1) * 2 + ks) * 64 + ln) * 8); Wi[ks] = *(const bf16x8*)(IUT + (((wave * 4 + ct + 1) * 2 + ks) * 64 + ln) * 8); }
; #pragma unroll
;                     for (int ks = 0; ks < 4; ++ks) Wg[ks] = *(const bf16x8*)(GUT + (((wave * 4 + ct + 1) * 4 + ks) * 64 + ln) * 8);
;                 }
;                 const f32x4 w0 = *(const f32x4*)(A.w0 + ch), a0 = *(const f32x4*)(A.a0 + ch), ka = *(const f32x4*)(A.k_a + ch), rk = *(const f32x4*)(A.r_k + ch);
;                 const f32x4 mur = *(const f32x4*)(A.mu + ch), muk = *(const f32x4*)(A.mu + 512 + ch), muv = *(const f32x4*)(A.mu + 1024 + ch);
;                 const unsigned char* rs = stg + fr * 144 + c4 * 2;
;                 const f32x4 r0 = bf4(*(const u32x2*)(rs)), r1 = bf4(*(const u32x2*)(rs + 144));
;                 const f32x4 k0 = bf4(*(const u32x2*)(rs + 17 * 144)), k1 = bf4(*(const u32x2*)(rs + 18 * 144));
;                 const f32x4 v0 = bf4(*(const u32x2*)(rs + 34 * 144)), v1 = bf4(*(const u32x2*)(rs + 35 * 144));
;                 const f32x4 rm = r1 + (r0 - r1) * mur, km = k1 + (k0 - k1) * muk, vm = v1 + (v0 - v1) * muv;
;                 f32x4 lw, ah;
; #pragma unroll
;                 for (int r = 0; r < 4; ++r) { lw[r] = -0.6065306597f * sigmoidf_(w0[r] + ad[r]); ah[r] = sigmoidf_(a0[r] + ai[r]); }
;                 const f32x4 kp = km * ((ah - 1.0f) * ka + 1.0f);
;                 const f32x4 pr3 = rm * kp * rk;
	v_lshlrev_b32_e32 v164, 16, v68
	v_and_b32_e32 v165, 0xffff0000, v68
	v_lshlrev_b32_e32 v166, 16, v69
	v_and_b32_e32 v167, 0xffff0000, v69
	v_lshlrev_b32_e32 v48, 16, v70
	v_and_b32_e32 v49, 0xffff0000, v70
	v_lshlrev_b32_e32 v50, 16, v71
	v_and_b32_e32 v51, 0xffff0000, v71
	s_nop 0
	s_nop 0
	s_waitcnt lgkmcnt(0)
	v_lshlrev_b32_e32 v178, 16, v40
	v_and_b32_e32 v179, 0xffff0000, v40
	v_lshlrev_b32_e32 v208, 16, v41
	v_and_b32_e32 v209, 0xffff0000, v41
	v_lshlrev_b32_e32 v40, 16, v42
	v_and_b32_e32 v41, 0xffff0000, v42
	v_lshlrev_b32_e32 v42, 16, v43
	v_and_b32_e32 v43, 0xffff0000, v43
	v_sub_f32_e32 v165, v165, v49
	v_sub_f32_e32 v164, v164, v48
	v_sub_f32_e32 v167, v167, v51
	v_sub_f32_e32 v166, v166, v50
	v_sub_f32_e32 v179, v179, v41
	v_sub_f32_e32 v178, v178, v40
	v_sub_f32_e32 v209, v209, v43
	v_sub_f32_e32 v208, v208, v42
	v_add_u32_e32 v68, 0x1000, v173
	ds_read2_b64 v[68:71], v68 offset0:100 offset1:118
	s_nop 0
	v_pk_fma_f32 v[160:161], v[176:177], v[166:167], v[50:51]
	v_pk_fma_f32 v[162:163], v[174:175], v[164:165], v[48:49]
	s_nop 0
	v_pk_fma_f32 v[164:165], v[198:199], v[208:209], v[42:43]
	v_pk_fma_f32 v[166:167], v[196:197], v[178:179], v[40:41]
	v_pk_add_f32 v[40:41], v[158:159], -1.0 op_sel_hi:[1,0]
	v_pk_add_f32 v[42:43], v[156:157], -1.0 op_sel_hi:[1,0]
	s_nop 0
	v_pk_fma_f32 v[40:41], v[202:203], v[40:41], 1.0 op_sel_hi:[1,1,0]
	v_pk_fma_f32 v[42:43], v[200:201], v[42:43], 1.0 op_sel_hi:[1,1,0]
	v_pk_mul_f32 v[40:41], v[40:41], v[164:165]
	v_pk_mul_f32 v[42:43], v[42:43], v[166:167]
	v_pk_mul_f32 v[40:41], v[160:161], v[40:41]
	v_pk_mul_f32 v[42:43], v[162:163], v[42:43]
	s_nop 0
	v_pk_mul_f32 v[40:41], v[206:207], v[40:41]
	v_pk_mul_f32 v[42:43], v[204:205], v[42:43]
	v_add_f32_e32 v40, v40, v41
	v_add_f32_e32 v42, v42, v43
	v_add_f32_e32 v40, v42, v40
	v_mov_b32_e32 v41, v40
	s_nop 1
	v_permlane32_swap_b32_e32 v40, v41
	v_add_f32_e32 v40, v40, v41
	v_mov_b32_e32 v41, v40
	s_nop 1
	v_permlane16_swap_b32_e32 v40, v41
	s_and_saveexec_b64 s[6:7], s[52:53]
	s_cbranch_execz .LBB0_357
	v_add_f32_e32 v40, v40, v41
	global_store_dword v[154:155], v40, off offset:8
.LBB0_357:
	s_or_b64 exec, exec, s[6:7]
	ds_read_b128 v[40:43], v172
	ds_read_b128 v[48:51], v172 offset:128
	v_add_u32_e32 v171, 48, v171
	s_nop 0
	s_nop 0
	s_waitcnt vmcnt(7) lgkmcnt(1)
	v_mfma_f32_16x16x32_bf16 v[40:43], v[72:75], v[40:43], 0
	s_nop 0
	s_nop 0
	s_waitcnt vmcnt(6) lgkmcnt(0)
	v_mfma_f32_16x16x32_bf16 v[48:51], v[60:63], v[48:51], 0
	ds_read_b128 v[174:177], v172 offset:64
	ds_read_b128 v[60:63], v172 offset:192
	s_nop 0
	s_nop 0
	s_waitcnt vmcnt(4) lgkmcnt(0)
	v_mfma_f32_16x16x32_bf16 v[60:63], v[80:83], v[60:63], v[48:51]
	ds_read_b128 v[80:83], v172 offset:320
	s_nop 2
	ds_read_b128 v[48:51], v172 offset:256
	s_nop 0
	s_nop 0
	s_waitcnt vmcnt(3) lgkmcnt(0)
	v_mfma_f32_16x16x32_bf16 v[48:51], v[88:91], v[48:51], 0
	s_nop 0
	s_waitcnt vmcnt(2)
	v_mfma_f32_16x16x32_bf16 v[48:51], v[84:87], v[80:83], v[48:51]
	ds_read_b128 v[80:83], v172 offset:384
	s_nop 0
	s_nop 0
	s_waitcnt vmcnt(1) lgkmcnt(0)
	v_mfma_f32_16x16x32_bf16 v[48:51], v[96:99], v[80:83], v[48:51]
	ds_read_b128 v[80:83], v172 offset:448
	v_add_u32_e32 v96, s34, v171
	v_ashrrev_i32_e32 v97, 31, v96
	s_nop 0
	s_nop 0
	s_waitcnt vmcnt(0) lgkmcnt(0)
	v_mfma_f32_16x16x32_bf16 v[88:91], v[92:95], v[80:83], v[48:51]
	v_lshl_add_u64 v[96:97], v[96:97], 2, s[24:25]
	v_mfma_f32_16x16x32_bf16 v[80:83], v[76:79], v[174:177], v[40:43]
	ds_read_b128 v[84:87], v210 offset:1472
	ds_read_b128 v[92:95], v210 offset:192
	ds_read_b128 v[48:51], v210 offset:1216
	ds_read_b128 v[40:43], v210 offset:960
	ds_read_b128 v[76:79], v210 offset:448
	ds_read_b128 v[72:75], v210 offset:704
	v_lshl_add_u32 v104, v171, 1, v170
	ds_read_b128 v[100:103], v210 offset:1728
	ds_read2_b64 v[96:99], v104 offset1:18
	s_nop 0
	s_nop 0
	s_waitcnt lgkmcnt(0)
	v_lshlrev_b32_e32 v168, 16, v96
	v_lshlrev_b32_e32 v174, 16, v98
	v_sub_f32_e32 v176, v168, v174
	v_and_b32_e32 v169, 0xffff0000, v96
	v_and_b32_e32 v175, 0xffff0000, v98
	v_sub_f32_e32 v177, v169, v175
	v_lshlrev_b32_e32 v170, 16, v97
	v_lshlrev_b32_e32 v172, 16, v99
	v_sub_f32_e32 v178, v170, v172
	v_add_u32_e32 v96, 0x800, v104
	v_and_b32_e32 v171, 0xffff0000, v97
	v_and_b32_e32 v173, 0xffff0000, v99
	ds_read2_b64 v[96:99], v96 offset0:50 offset1:68
	v_sub_f32_e32 v179, v171, v173
	v_add_u32_e32 v104, 0x1000, v104
	ds_read2_b64 v[104:107], v104 offset0:100 offset1:118
	s_nop 0
	s_nop 0
	s_waitcnt lgkmcnt(1)
	v_lshlrev_b32_e32 v196, 16, v96
	v_and_b32_e32 v197, 0xffff0000, v96
	v_lshlrev_b32_e32 v198, 16, v97
	v_and_b32_e32 v199, 0xffff0000, v97
	v_lshlrev_b32_e32 v96, 16, v98
	v_and_b32_e32 v97, 0xffff0000, v98
	v_lshlrev_b32_e32 v98, 16, v99
	v_and_b32_e32 v99, 0xffff0000, v99
	v_sub_f32_e32 v197, v197, v97
	v_sub_f32_e32 v196, v196, v96
	v_sub_f32_e32 v199, v199, v99
	v_sub_f32_e32 v198, v198, v98
	s_nop 0
	v_add_f32_e32 v60, v60, v92
	v_mul_f32_e32 v60, 0xbfb8aa3b, v60
	v_exp_f32_e32 v60, v60
	s_nop 0
	v_pk_fma_f32 v[172:173], v[78:79], v[178:179], v[172:173]
	v_pk_fma_f32 v[174:175], v[76:77], v[176:177], v[174:175]
	s_nop 0
	v_pk_fma_f32 v[176:177], v[74:75], v[198:199], v[98:99]
	v_add_f32_e32 v60, 1.0, v60
	v_rcp_f32_e32 v168, v60
	v_add_f32_e32 v60, v61, v93
	v_mul_f32_e32 v60, 0xbfb8aa3b, v60
	v_exp_f32_e32 v60, v60
	v_pk_fma_f32 v[178:179], v[72:73], v[196:197], v[96:97]
	v_add_f32_e32 v60, 1.0, v60
	v_rcp_f32_e32 v169, v60
	v_add_f32_e32 v60, v62, v94
	v_mul_f32_e32 v60, 0xbfb8aa3b, v60
	v_exp_f32_e32 v60, v60
	s_nop 0
	v_add_f32_e32 v60, 1.0, v60
	v_rcp_f32_e32 v170, v60
	v_add_f32_e32 v60, v63, v95
	v_mul_f32_e32 v60, 0xbfb8aa3b, v60
	v_exp_f32_e32 v60, v60
	v_pk_add_f32 v[62:63], v[168:169], -1.0 op_sel_hi:[1,0]
	v_add_f32_e32 v60, 1.0, v60
	v_rcp_f32_e32 v171, v60
	v_pk_fma_f32 v[48:49], v[48:49], v[62:63], 1.0 op_sel_hi:[1,1,0]
	v_pk_add_f32 v[60:61], v[170:171], -1.0 op_sel_hi:[1,0]
	s_nop 0
	v_pk_fma_f32 v[50:51], v[50:51], v[60:61], 1.0 op_sel_hi:[1,1,0]
	v_pk_mul_f32 v[48:49], v[48:49], v[178:179]
	v_pk_mul_f32 v[50:51], v[50:51], v[176:177]
	v_pk_mul_f32 v[48:49], v[174:175], v[48:49]
	v_pk_mul_f32 v[50:51], v[172:173], v[50:51]
	v_pk_mul_f32 v[40:41], v[40:41], v[48:49]
	v_pk_mul_f32 v[42:43], v[42:43], v[50:51]
	v_add_f32_e32 v40, v40, v41
	v_add_f32_e32 v41, v42, v43
	v_add_f32_e32 v40, v40, v41
	v_mov_b32_e32 v41, v40
	s_nop 1
	v_permlane32_swap_b32_e32 v40, v41
	v_add_f32_e32 v40, v40, v41
	v_mov_b32_e32 v41, v40
	s_nop 1
	v_permlane16_swap_b32_e32 v40, v41
	s_and_saveexec_b64 s[6:7], s[52:53]
	s_cbranch_execz .LBB0_359
	v_add_f32_e32 v40, v40, v41
	global_store_dword v[154:155], v40, off offset:12

; __global__ void __launch_bounds__(512, 2) mega_fwd(Args a) {
	.amdhsa_kernel _Z8mega_fwd4Args
		.amdhsa_group_segment_fixed_size 0
		.amdhsa_private_segment_fixed_size 0
		.amdhsa_kernarg_size 504
		.amdhsa_user_sgpr_count 2
		.amdhsa_user_sgpr_dispatch_ptr 0
		.amdhsa_user_sgpr_queue_ptr 0
		.amdhsa_user_sgpr_kernarg_segment_ptr 1
		.amdhsa_user_sgpr_dispatch_id 0
		.amdhsa_user_sgpr_kernarg_preload_length 0
		.amdhsa_user_sgpr_kernarg_preload_offset 0
		.amdhsa_user_sgpr_private_segment_size 0
		.amdhsa_uses_dynamic_stack 0
		.amdhsa_enable_private_segment 0
		.amdhsa_system_sgpr_workgroup_id_x 1
		.amdhsa_system_sgpr_workgroup_id_y 0
		.amdhsa_system_sgpr_workgroup_id_z 0
		.amdhsa_system_sgpr_workgroup_info 0
		.amdhsa_system_vgpr_workitem_id 2
		.amdhsa_next_free_vgpr 248
		.amdhsa_next_free_sgpr 102
		.amdhsa_accum_offset 248
		.amdhsa_reserve_vcc 1
		.amdhsa_float_round_mode_32 0
		.amdhsa_float_round_mode_16_64 0
		.amdhsa_float_denorm_mode_32 3
		.amdhsa_float_denorm_mode_16_64 3
		.amdhsa_dx10_clamp 1
		.amdhsa_ieee_mode 1
		.amdhsa_fp16_overflow 0
		.amdhsa_tg_split 0
		.amdhsa_exception_fp_ieee_invalid_op 0
		.amdhsa_exception_fp_denorm_src 0
		.amdhsa_exception_fp_ieee_div_zero 0
		.amdhsa_exception_fp_ieee_overflow 0
		.amdhsa_exception_fp_ieee_underflow 0
		.amdhsa_exception_fp_ieee_inexact 0
		.amdhsa_exception_int_div_zero 0
	.end_amdhsa_kernel

; __global__ void __launch_bounds__(512, 2) mega_fwd(Args a) {
amdhsa.kernels:
  - .agpr_count:     0
    .args:
      - .offset:         0
        .size:           248
        .value_kind:     by_value
      - .offset:         248
        .size:           4
        .value_kind:     hidden_block_count_x
      - .offset:         252
        .size:           4
        .value_kind:     hidden_block_count_y
      - .offset:         256
        .size:           4
        .value_kind:     hidden_block_count_z
      - .offset:         260
        .size:           2
        .value_kind:     hidden_group_size_x
      - .offset:         262
        .size:           2
        .value_kind:     hidden_group_size_y
      - .offset:         264
        .size:           2
        .value_kind:     hidden_group_size_z
      - .offset:         266
        .size:           2
        .value_kind:     hidden_remainder_x
      - .offset:         268
        .size:           2
        .value_kind:     hidden_remainder_y
      - .offset:         270
        .size:           2
        .value_kind:     hidden_remainder_z
      - .offset:         288
        .size:           8
        .value_kind:     hidden_global_offset_x
      - .offset:         296
        .size:           8
        .value_kind:     hidden_global_offset_y
      - .offset:         304
        .size:           8
        .value_kind:     hidden_global_offset_z
      - .offset:         312
        .size:           2
        .value_kind:     hidden_grid_dims
      - .offset:         336
        .size:           8
        .value_kind:     hidden_multigrid_sync_arg
      - .offset:         368
        .size:           4
        .value_kind:     hidden_dynamic_lds_size
    .group_segment_fixed_size: 0
    .kernarg_segment_align: 8
    .kernarg_segment_size: 504
    .language:       OpenCL C
    .language_version:
      - 2
      - 0
    .max_flat_workgroup_size: 512
    .name:           _Z8mega_fwd4Args
    .private_segment_fixed_size: 0
    .sgpr_count:     108
    .sgpr_spill_count: 151
    .symbol:         _Z8mega_fwd4Args.kd
    .uniform_work_group_size: 1
    .uses_dynamic_stack: false
    .vgpr_count:     248
    .vgpr_spill_count: 0
    .wavefront_size: 64
